# diff-attention wave-half stagger tuned: s_sleep 5 instead of 3
# baseline (speedup 1.0000x reference)
;     ...
; #pragma unroll
;                 for (int r = 0; r < 16; ++r) { s0[r] = __builtin_amdgcn_exp2f(fmaf(s0[r], C2S, -mnew)); s1[r] = __builtin_amdgcn_exp2f(fmaf(s1[r], C2S, -mnew)); ps += s0[r] + s1[r]; }
;             }
;             lsum = lsum * alpha_l + ps;
;     ...
;         __syncthreads();
.LBB0_623:
	v_add_f32_e32 v187, v64, v80
	v_add_f32_e32 v187, 0, v187
	v_add_f32_e32 v191, v65, v81
	v_add_f32_e32 v187, v191, v187
	v_add_f32_e32 v191, v66, v82
	v_add_f32_e32 v187, v191, v187
	v_add_f32_e32 v191, v67, v83
	v_add_f32_e32 v187, v191, v187
	v_add_f32_e32 v191, v68, v84
	v_add_f32_e32 v187, v191, v187
	v_add_f32_e32 v191, v69, v85
	v_add_f32_e32 v187, v191, v187
	v_add_f32_e32 v191, v70, v86
	v_add_f32_e32 v187, v191, v187
	v_add_f32_e32 v191, v71, v87
	v_add_f32_e32 v187, v191, v187
	v_add_f32_e32 v191, v72, v88
	v_add_f32_e32 v187, v191, v187
	v_add_f32_e32 v191, v73, v89
	v_add_f32_e32 v187, v191, v187
	v_add_f32_e32 v191, v74, v90
	v_add_f32_e32 v187, v191, v187
	v_add_f32_e32 v191, v75, v91
	v_add_f32_e32 v187, v191, v187
	v_add_f32_e32 v191, v76, v92
	v_add_f32_e32 v187, v191, v187
	v_add_f32_e32 v191, v77, v93
	v_add_f32_e32 v187, v191, v187
	v_add_f32_e32 v191, v78, v94
	v_add_f32_e32 v187, v191, v187
	v_add_f32_e32 v191, v79, v95
	v_add_f32_e32 v187, v191, v187
	v_fmac_f32_e32 v187, v190, v188
	s_and_b64 vcc, exec, s[42:43]
	s_waitcnt lgkmcnt(0)
	s_barrier
	v_readfirstlane_b32 s100, v194
	s_bitcmp1_b32 s100, 8
	s_cbranch_scc0 .Lda_stag0
	s_sleep 5


;     ...
; #pragma unroll
;                 for (int r = 0; r < 16; ++r) { s0[r] = __builtin_amdgcn_exp2f(fmaf(s0[r], C2S, -mnew)); s1[r] = __builtin_amdgcn_exp2f(fmaf(s1[r], C2S, -mnew)); ps += s0[r] + s1[r]; }
;             }
;             lsum = lsum * alpha_l + ps;
;     ...
;         __syncthreads();
.LBB0_636:
	v_add_f32_e32 v96, v96, v101
	v_add_f32_e32 v96, 0, v96
	v_add_f32_e32 v97, v97, v105
	v_add_f32_e32 v96, v97, v96
	v_add_f32_e32 v97, v98, v106
	v_add_f32_e32 v96, v97, v96
	v_add_f32_e32 v97, v99, v107
	v_add_f32_e32 v96, v97, v96
	v_add_f32_e32 v97, v100, v112
	v_add_f32_e32 v96, v97, v96
	v_add_f32_e32 v97, v102, v113
	v_add_f32_e32 v96, v97, v96
	v_add_f32_e32 v97, v103, v114
	v_add_f32_e32 v96, v97, v96
	v_add_f32_e32 v97, v104, v115
	v_add_f32_e32 v96, v97, v96
	v_add_f32_e32 v97, v108, v120
	v_add_f32_e32 v96, v97, v96
	v_add_f32_e32 v97, v109, v121
	v_add_f32_e32 v96, v97, v96
	v_add_f32_e32 v97, v110, v122
	v_add_f32_e32 v96, v97, v96
	v_add_f32_e32 v97, v111, v123
	v_add_f32_e32 v96, v97, v96
	v_add_f32_e32 v97, v116, v124
	v_add_f32_e32 v96, v97, v96
	v_add_f32_e32 v97, v117, v125
	v_add_f32_e32 v96, v97, v96
	v_add_f32_e32 v97, v118, v126
	v_add_f32_e32 v96, v97, v96
	v_add_f32_e32 v97, v119, v127
	v_add_f32_e32 v96, v97, v96
	v_fmac_f32_e32 v96, v187, v189
	v_mov_b32_e32 v187, v96
	s_waitcnt lgkmcnt(0)
	s_barrier
	v_readfirstlane_b32 s100, v194
	s_bitcmp1_b32 s100, 8
	s_cbranch_scc0 .Lda_stag1
	s_sleep 5

